# in-proj last-round K-split hand-over only when the partial round is small (layer 1: 24 tiles); layer 0 keeps whole tiles so its weight conversion keeps its workgroups (on v86)
# baseline (speedup 1.0000x reference)
.LBB0_81:
	s_add_i32 s62, s62, 1
	s_mul_i32 s4, s62, s31
	s_mul_hi_u32 s5, s62, s82
	s_add_i32 s5, s5, s4
	s_mul_i32 s4, s62, s82
	s_add_u32 s4, s4, s2
	s_addc_u32 s5, s5, s3
	s_waitcnt lgkmcnt(0)
	s_mov_b32 s99, 0
	s_add_i32 s100, s88, -1
	s_lshr_b32 s100, s100, 8
	s_cmp_lg_u32 s62, s100
	s_cbranch_scc1 .Lmy_ik_nosplit
	s_lshl_b32 s101, s100, 8
	s_sub_i32 s100, s88, s101
	s_cmpk_gt_i32 s100, 48
	s_cbranch_scc1 .Lmy_ik_nosplit
	s_lshl_b32 s100, s100, 1
	s_mov_b32 s4, s88
	s_cmp_lt_u32 s2, s100
	s_cbranch_scc0 .Lmy_ik_nosplit
	s_lshr_b32 s4, s2, 1
	s_add_i32 s4, s4, s101
	s_and_b32 s99, s2, 1
	s_add_i32 s99, s99, 1
